# MIX1 chunk-state items rebalanced: scan workgroups 12 / 11 items instead of 13, freed items as sixth item on non-scan workgroups
# speedup vs baseline: 1.0058x; 1.0058x over previous
.LBB0_411:
	s_load_dwordx4 s[28:31], s[0:1], 0x78
	s_load_dwordx2 s[4:5], s[0:1], 0x90
	s_load_dwordx4 s[36:39], s[0:1], 0xa0
	s_mov_b64 s[6:7], -1
	s_and_b64 vcc, exec, s[42:43]
	s_cbranch_vccz .LBB0_413
	v_readlane_b32 s6, v254, 39
	v_readlane_b32 s7, v254, 40
	s_and_b64 s[6:7], s[6:7], exec
	s_movk_i32 s7, 0x2e8
	s_movk_i32 s6, 0x8e
	s_cselect_b32 s6, 0x7c, s6
	s_cselect_b32 s7, s7, 0x2d6
	s_add_i32 s8, s7, s6
	s_mul_i32 s9, s94, 12
	s_add_i32 s8, s8, s9
	s_sub_i32 s9, s94, 64
	s_cmp_lt_u32 s9, s6
	s_mul_i32 s13, s9, 5
	s_cselect_b32 s12, 6, 5
	s_add_i32 s7, s13, s7
	s_min_u32 s6, s9, s6
	s_add_i32 s6, s7, s6
	s_add_i32 s7, s6, s12
	s_add_i32 s9, s8, 0xfffff8f4
	s_addk_i32 s8, 0xf900
	s_cmpk_lt_u32 s94, 0xd4
	s_cselect_b32 s34, s7, s8
	s_cselect_b32 s51, s6, s9
	s_mov_b64 s[6:7], 0
.LBB0_413:
	s_andn2_b64 vcc, exec, s[6:7]
	s_cbranch_vccnz .LBB0_415
	s_sub_i32 s6, s94, s60
	s_add_i32 s8, s6, 0x42
	s_and_b64 s[6:7], s[10:11], exec
	s_cselect_b32 s6, s94, s8
	s_mul_i32 s7, s6, 6
	s_mul_i32 s9, s6, 11
	s_mul_i32 s11, s6, 12
	s_add_i32 s8, s7, 6
	s_sub_i32 s10, s11, 36
	s_sub_i32 s11, s11, 48
	s_add_i32 s12, s9, 11
	s_cmp_lt_i32 s6, 8
	s_cselect_b32 s8, s8, s10
	s_cselect_b32 s10, s7, s11
	v_readlane_b32 s6, v254, 39
	v_readlane_b32 s7, v254, 40
	s_and_b64 s[6:7], s[6:7], exec
	s_cselect_b32 s34, s8, s12
	s_cselect_b32 s51, s10, s9
